# v91 + P7 row-stat exchange polls without s_sleep between polls
# baseline (speedup 1.0000x reference)
; __device__ __forceinline__ void wait_count(unsigned* cnt, unsigned want) {
;     for (unsigned sp = 0; sp < (1u << 22); ++sp) { if (__hip_atomic_load(cnt, __ATOMIC_RELAXED, __HIP_MEMORY_SCOPE_AGENT) >= want) break; __builtin_amdgcn_s_sleep(2); }
; }
; __device__ __forceinline__ void down_sample_tile(Frame& F, int tile, float* SS2, unsigned* cntb, float* YO) {
;     ...
;     if (F.tid == 0) { __hip_atomic_fetch_add(cnt, 1u, __ATOMIC_RELAXED, __HIP_MEMORY_SCOPE_AGENT); wait_count(cnt, 16u); }
.LBB0_1033:
	global_load_dword v24, v23, s[8:9] sc1
	s_mov_b64 s[12:13], -1
	s_waitcnt vmcnt(0)
	v_cmp_lt_u32_e32 vcc, 15, v24
	s_cbranch_vccnz .LBB0_1032
	s_sleep 0
	global_load_dword v24, v23, s[8:9] sc1
	s_waitcnt vmcnt(0)
	v_cmp_gt_u32_e32 vcc, 16, v24
	s_cbranch_vccz .LBB0_1032
	s_sleep 0
	global_load_dword v24, v23, s[8:9] sc1
	s_waitcnt vmcnt(0)
	v_cmp_gt_u32_e32 vcc, 16, v24
	s_cbranch_vccz .LBB0_1032
	s_sleep 0
	global_load_dword v24, v23, s[8:9] sc1
	s_waitcnt vmcnt(0)
	v_cmp_gt_u32_e32 vcc, 16, v24
	s_cbranch_vccz .LBB0_1032
	s_sleep 0
	global_load_dword v24, v23, s[8:9] sc1
	s_waitcnt vmcnt(0)
	v_cmp_gt_u32_e32 vcc, 16, v24
	s_cbranch_vccz .LBB0_1032
	s_sleep 0
	global_load_dword v24, v23, s[8:9] sc1
	s_waitcnt vmcnt(0)
	v_cmp_gt_u32_e32 vcc, 16, v24
	s_cbranch_vccz .LBB0_1032
	s_sleep 0
	global_load_dword v24, v23, s[8:9] sc1
	s_waitcnt vmcnt(0)
	v_cmp_gt_u32_e32 vcc, 16, v24
	s_cbranch_vccz .LBB0_1032
	s_sleep 0
	global_load_dword v24, v23, s[8:9] sc1
	s_waitcnt vmcnt(0)
	v_cmp_gt_u32_e32 vcc, 16, v24
	s_cbranch_vccz .LBB0_1032
	s_add_i32 s20, s20, -8
	s_cmp_eq_u32 s20, 0
	s_cselect_b64 s[12:13], -1, 0
	s_sleep 0
	s_branch .LBB0_1032

; __device__ __forceinline__ void wait_count(unsigned* cnt, unsigned want) {
;     for (unsigned sp = 0; sp < (1u << 22); ++sp) { if (__hip_atomic_load(cnt, __ATOMIC_RELAXED, __HIP_MEMORY_SCOPE_AGENT) >= want) break; __builtin_amdgcn_s_sleep(2); }
; }
;     __device__ __forceinline__ void operator()(pg8::f32x4 (&acc)[2][2][4][2], const Unit& u, int wr, int wc, int fr, int fq) const {
;     ...
;         wait_count(c, 32u);
.LBB0_1092:
	global_load_dword v2, v133, s[4:5] sc1
	s_mov_b64 s[30:31], -1
	s_waitcnt vmcnt(0)
	v_cmp_lt_u32_e32 vcc, 31, v2
	s_cbranch_vccnz .LBB0_1091
	s_sleep 0
	global_load_dword v2, v133, s[4:5] sc1
	s_waitcnt vmcnt(0)
	v_cmp_gt_u32_e32 vcc, 32, v2
	s_cbranch_vccz .LBB0_1091
	s_sleep 0
	global_load_dword v2, v133, s[4:5] sc1
	s_waitcnt vmcnt(0)
	v_cmp_gt_u32_e32 vcc, 32, v2
	s_cbranch_vccz .LBB0_1091
	s_sleep 0
	global_load_dword v2, v133, s[4:5] sc1
	s_waitcnt vmcnt(0)
	v_cmp_gt_u32_e32 vcc, 32, v2
	s_cbranch_vccz .LBB0_1091
	s_sleep 0
	global_load_dword v2, v133, s[4:5] sc1
	s_waitcnt vmcnt(0)
	v_cmp_gt_u32_e32 vcc, 32, v2
	s_cbranch_vccz .LBB0_1091
	s_sleep 0
	global_load_dword v2, v133, s[4:5] sc1
	s_waitcnt vmcnt(0)
	v_cmp_gt_u32_e32 vcc, 32, v2
	s_cbranch_vccz .LBB0_1091
	s_sleep 0
	global_load_dword v2, v133, s[4:5] sc1
	s_waitcnt vmcnt(0)
	v_cmp_gt_u32_e32 vcc, 32, v2
	s_cbranch_vccz .LBB0_1091
	s_sleep 0
	global_load_dword v2, v133, s[4:5] sc1
	s_waitcnt vmcnt(0)
	v_cmp_gt_u32_e32 vcc, 32, v2
	s_cbranch_vccz .LBB0_1091
	s_add_i32 s33, s33, -8
	s_cmp_eq_u32 s33, 0
	s_cselect_b64 s[30:31], -1, 0
	s_sleep 0
	s_branch .LBB0_1091

; __device__ __forceinline__ void wait_count(unsigned* cnt, unsigned want) {
;     for (unsigned sp = 0; sp < (1u << 22); ++sp) { if (__hip_atomic_load(cnt, __ATOMIC_RELAXED, __HIP_MEMORY_SCOPE_AGENT) >= want) break; __builtin_amdgcn_s_sleep(2); }
; }
; __device__ __forceinline__ void down_sample_tile(Frame& F, int tile, float* SS2, unsigned* cntb, float* YO) {
;     ...
;     if (F.tid == 0) { __hip_atomic_fetch_add(cnt, 1u, __ATOMIC_RELAXED, __HIP_MEMORY_SCOPE_AGENT); wait_count(cnt, 16u); }
.LBB0_1148:
	global_load_dword v22, v55, s[4:5] sc1
	s_mov_b64 s[8:9], -1
	s_waitcnt vmcnt(0)
	v_cmp_lt_u32_e32 vcc, 15, v22
	s_cbranch_vccnz .LBB0_1147
	s_sleep 0
	global_load_dword v22, v55, s[4:5] sc1
	s_waitcnt vmcnt(0)
	v_cmp_gt_u32_e32 vcc, 16, v22
	s_cbranch_vccz .LBB0_1147
	s_sleep 0
	global_load_dword v22, v55, s[4:5] sc1
	s_waitcnt vmcnt(0)
	v_cmp_gt_u32_e32 vcc, 16, v22
	s_cbranch_vccz .LBB0_1147
	s_sleep 0
	global_load_dword v22, v55, s[4:5] sc1
	s_waitcnt vmcnt(0)
	v_cmp_gt_u32_e32 vcc, 16, v22
	s_cbranch_vccz .LBB0_1147
	s_sleep 0
	global_load_dword v22, v55, s[4:5] sc1
	s_waitcnt vmcnt(0)
	v_cmp_gt_u32_e32 vcc, 16, v22
	s_cbranch_vccz .LBB0_1147
	s_sleep 0
	global_load_dword v22, v55, s[4:5] sc1
	s_waitcnt vmcnt(0)
	v_cmp_gt_u32_e32 vcc, 16, v22
	s_cbranch_vccz .LBB0_1147
	s_sleep 0
	global_load_dword v22, v55, s[4:5] sc1
	s_waitcnt vmcnt(0)
	v_cmp_gt_u32_e32 vcc, 16, v22
	s_cbranch_vccz .LBB0_1147
	s_sleep 0
	global_load_dword v22, v55, s[4:5] sc1
	s_waitcnt vmcnt(0)
	v_cmp_gt_u32_e32 vcc, 16, v22
	s_cbranch_vccz .LBB0_1147
	s_add_i32 s10, s10, -8
	s_cmp_eq_u32 s10, 0
	s_cselect_b64 s[8:9], -1, 0
	s_sleep 0
	s_branch .LBB0_1147

; __device__ __forceinline__ void wait_count(unsigned* cnt, unsigned want) {
;     for (unsigned sp = 0; sp < (1u << 22); ++sp) { if (__hip_atomic_load(cnt, __ATOMIC_RELAXED, __HIP_MEMORY_SCOPE_AGENT) >= want) break; __builtin_amdgcn_s_sleep(2); }
; }
; __device__ __forceinline__ void down_sample_tile(Frame& F, int tile, float* SS2, unsigned* cntb, float* YO) {
;     ...
;     if (F.tid == 0) { __hip_atomic_fetch_add(cnt, 1u, __ATOMIC_RELAXED, __HIP_MEMORY_SCOPE_AGENT); wait_count(cnt, 16u); }
.LBB0_1169:
	global_load_dword v23, v22, s[2:3] sc1
	s_mov_b64 s[6:7], -1
	s_waitcnt vmcnt(0)
	v_cmp_lt_u32_e32 vcc, 15, v23
	s_cbranch_vccnz .LBB0_1168
	s_sleep 0
	global_load_dword v23, v22, s[2:3] sc1
	s_waitcnt vmcnt(0)
	v_cmp_gt_u32_e32 vcc, 16, v23
	s_cbranch_vccz .LBB0_1168
	s_sleep 0
	global_load_dword v23, v22, s[2:3] sc1
	s_waitcnt vmcnt(0)
	v_cmp_gt_u32_e32 vcc, 16, v23
	s_cbranch_vccz .LBB0_1168
	s_sleep 0
	global_load_dword v23, v22, s[2:3] sc1
	s_waitcnt vmcnt(0)
	v_cmp_gt_u32_e32 vcc, 16, v23
	s_cbranch_vccz .LBB0_1168
	s_sleep 0
	global_load_dword v23, v22, s[2:3] sc1
	s_waitcnt vmcnt(0)
	v_cmp_gt_u32_e32 vcc, 16, v23
	s_cbranch_vccz .LBB0_1168
	s_sleep 0
	global_load_dword v23, v22, s[2:3] sc1
	s_waitcnt vmcnt(0)
	v_cmp_gt_u32_e32 vcc, 16, v23
	s_cbranch_vccz .LBB0_1168
	s_sleep 0
	global_load_dword v23, v22, s[2:3] sc1
	s_waitcnt vmcnt(0)
	v_cmp_gt_u32_e32 vcc, 16, v23
	s_cbranch_vccz .LBB0_1168
	s_sleep 0
	global_load_dword v23, v22, s[2:3] sc1
	s_waitcnt vmcnt(0)
	v_cmp_gt_u32_e32 vcc, 16, v23
	s_cbranch_vccz .LBB0_1168
	s_add_i32 s8, s8, -8
	s_cmp_eq_u32 s8, 0
	s_cselect_b64 s[6:7], -1, 0
	s_sleep 0
	s_branch .LBB0_1168
